# ffn-up K-loop head moved to an 8-byte boundary, following code kept at its previous alignment
# baseline (speedup 1.0000x reference)
.LBB0_92:
	s_add_u32 s8, s6, 0xfffc0080
	s_addc_u32 s9, s7, -1
	s_add_i32 s35, 0, 0x10000
	s_cmp_eq_u32 s59, 12
	s_cselect_b32 s11, s5, s9
	s_cselect_b32 s10, s24, s8
	v_add_u32_e32 v140, s35, v165
	s_cselect_b32 s9, s47, s58
	s_cselect_b32 s8, s51, s53
	s_add_i32 s74, 0, 0x14000
	ds_read_b128 v[142:145], v140
	ds_read_b128 v[146:149], v140 offset:1024
	ds_read_b128 v[150:153], v140 offset:2048
	ds_read_b128 v[154:157], v140 offset:3072
	v_add_u32_e32 v140, s74, v165
	ds_read_b128 v[158:161], v140
	ds_read_b128 v[168:171], v140 offset:1024
	ds_read_b128 v[172:175], v140 offset:2048
	ds_read_b128 v[176:179], v140 offset:3072
	v_lshl_add_u64 v[162:163], s[6:7], 0, v[136:137]
	s_add_i32 m0, s27, 0xc000
	ds_read_b128 v[180:183], v166
	ds_read_b128 v[184:187], v166 offset:1024
	ds_read_b128 v[188:191], v166 offset:2048
	ds_read_b128 v[192:195], v166 offset:3072
	ds_read_b128 v[200:203], v166 offset:4096
	ds_read_b128 v[206:209], v166 offset:5120
	ds_read_b128 v[210:213], v166 offset:6144
	ds_read_b128 v[214:217], v166 offset:7168
	global_load_lds_dwordx4 v[162:163], off
	v_lshl_add_u64 v[162:163], s[6:7], 0, v[138:139]
	s_add_i32 m0, s27, 0xe000
	s_nop 0
	global_load_lds_dwordx4 v[162:163], off
	s_waitcnt vmcnt(8)
	s_waitcnt lgkmcnt(0)
	s_barrier
	v_mfma_f32_16x16x32_bf16 v[124:127], v[142:145], v[180:183], v[124:127]
	s_setprio 1
	v_mfma_f32_16x16x32_bf16 v[120:123], v[150:153], v[180:183], v[120:123]
	v_mfma_f32_16x16x32_bf16 v[108:111], v[142:145], v[188:191], v[108:111]
	v_mfma_f32_16x16x32_bf16 v[104:107], v[150:153], v[188:191], v[104:107]
	v_mfma_f32_16x16x32_bf16 v[92:95], v[142:145], v[200:203], v[92:95]
	v_mfma_f32_16x16x32_bf16 v[88:91], v[150:153], v[200:203], v[88:91]
	v_mfma_f32_16x16x32_bf16 v[76:79], v[142:145], v[210:213], v[76:79]
	v_mfma_f32_16x16x32_bf16 v[72:75], v[150:153], v[210:213], v[72:75]
	v_mfma_f32_16x16x32_bf16 v[124:127], v[146:149], v[184:187], v[124:127]
	v_mfma_f32_16x16x32_bf16 v[120:123], v[154:157], v[184:187], v[120:123]
	v_mfma_f32_16x16x32_bf16 v[108:111], v[146:149], v[192:195], v[108:111]
	v_mfma_f32_16x16x32_bf16 v[104:107], v[154:157], v[192:195], v[104:107]
	v_mfma_f32_16x16x32_bf16 v[92:95], v[146:149], v[206:209], v[92:95]
	v_mfma_f32_16x16x32_bf16 v[88:91], v[154:157], v[206:209], v[88:91]
	v_mfma_f32_16x16x32_bf16 v[76:79], v[146:149], v[214:217], v[76:79]
	v_mfma_f32_16x16x32_bf16 v[72:75], v[154:157], v[214:217], v[72:75]
	v_mfma_f32_16x16x32_bf16 v[116:119], v[158:161], v[180:183], v[116:119]
	v_mfma_f32_16x16x32_bf16 v[112:115], v[172:175], v[180:183], v[112:115]
	v_mfma_f32_16x16x32_bf16 v[100:103], v[158:161], v[188:191], v[100:103]
	v_mfma_f32_16x16x32_bf16 v[96:99], v[172:175], v[188:191], v[96:99]
	v_mfma_f32_16x16x32_bf16 v[84:87], v[158:161], v[200:203], v[84:87]
	v_mfma_f32_16x16x32_bf16 v[80:83], v[172:175], v[200:203], v[80:83]
	v_mfma_f32_16x16x32_bf16 v[68:71], v[158:161], v[210:213], v[68:71]
	v_mfma_f32_16x16x32_bf16 v[64:67], v[172:175], v[210:213], v[64:67]
	v_mfma_f32_16x16x32_bf16 v[116:119], v[168:171], v[184:187], v[116:119]
	v_mfma_f32_16x16x32_bf16 v[112:115], v[176:179], v[184:187], v[112:115]
	v_mfma_f32_16x16x32_bf16 v[100:103], v[168:171], v[192:195], v[100:103]
	v_mfma_f32_16x16x32_bf16 v[96:99], v[176:179], v[192:195], v[96:99]
	v_mfma_f32_16x16x32_bf16 v[84:87], v[168:171], v[206:209], v[84:87]
	v_mfma_f32_16x16x32_bf16 v[80:83], v[176:179], v[206:209], v[80:83]
	v_mfma_f32_16x16x32_bf16 v[68:71], v[168:171], v[214:217], v[68:71]
	v_mfma_f32_16x16x32_bf16 v[64:67], v[176:179], v[214:217], v[64:67]
	s_barrier
	s_setprio 0
	s_add_i32 s35, s35, s13
	v_lshl_add_u64 v[162:163], s[8:9], 0, v[132:133]
	s_mov_b32 m0, s35
	ds_read_b128 v[180:183], v166 offset:16384
	ds_read_b128 v[184:187], v166 offset:17408
	ds_read_b128 v[188:191], v166 offset:18432
	ds_read_b128 v[192:195], v166 offset:19456
	ds_read_b128 v[200:203], v166 offset:20480
	ds_read_b128 v[206:209], v166 offset:21504
	ds_read_b128 v[210:213], v166 offset:22528
	ds_read_b128 v[214:217], v166 offset:23552
	global_load_lds_dwordx4 v[162:163], off
	s_add_i32 m0, s35, 0x2000
	s_add_u32 s60, s8, 0x40000
	v_lshl_add_u64 v[196:197], s[8:9], 0, v[128:129]
	s_addc_u32 s61, s9, 0
	s_add_i32 s35, s74, s13
	global_load_lds_dwordx4 v[196:197], off
	v_lshl_add_u64 v[198:199], s[60:61], 0, v[132:133]
	s_mov_b32 m0, s35
	v_lshl_add_u64 v[204:205], s[10:11], 0, v[130:131]
	global_load_lds_dwordx4 v[198:199], off
	v_lshl_add_u64 v[198:199], s[60:61], 0, v[128:129]
	s_add_i32 m0, s35, 0x2000
	s_nop 0
	global_load_lds_dwordx4 v[198:199], off
	v_lshl_add_u64 v[198:199], s[10:11], 0, v[134:135]
	s_mov_b32 m0, s27
	s_nop 0
	global_load_lds_dwordx4 v[198:199], off
	s_mov_b32 m0, s28
	s_nop 0
	global_load_lds_dwordx4 v[204:205], off
	s_waitcnt vmcnt(8)
	s_waitcnt lgkmcnt(0)
	s_barrier
	v_mfma_f32_16x16x32_bf16 v[60:63], v[142:145], v[180:183], v[60:63]
	s_setprio 1
	v_mfma_f32_16x16x32_bf16 v[56:59], v[150:153], v[180:183], v[56:59]
	v_mfma_f32_16x16x32_bf16 v[44:47], v[142:145], v[188:191], v[44:47]
	v_mfma_f32_16x16x32_bf16 v[40:43], v[150:153], v[188:191], v[40:43]
	v_mfma_f32_16x16x32_bf16 v[28:31], v[142:145], v[200:203], v[28:31]
	v_mfma_f32_16x16x32_bf16 v[24:27], v[150:153], v[200:203], v[24:27]
	v_mfma_f32_16x16x32_bf16 v[12:15], v[142:145], v[210:213], v[12:15]
	v_mfma_f32_16x16x32_bf16 v[8:11], v[150:153], v[210:213], v[8:11]
	v_mfma_f32_16x16x32_bf16 v[60:63], v[146:149], v[184:187], v[60:63]
	v_mfma_f32_16x16x32_bf16 v[56:59], v[154:157], v[184:187], v[56:59]
	v_mfma_f32_16x16x32_bf16 v[44:47], v[146:149], v[192:195], v[44:47]
	v_mfma_f32_16x16x32_bf16 v[40:43], v[154:157], v[192:195], v[40:43]
	v_mfma_f32_16x16x32_bf16 v[28:31], v[146:149], v[206:209], v[28:31]
	v_mfma_f32_16x16x32_bf16 v[24:27], v[154:157], v[206:209], v[24:27]
	v_mfma_f32_16x16x32_bf16 v[12:15], v[146:149], v[214:217], v[12:15]
	v_mfma_f32_16x16x32_bf16 v[8:11], v[154:157], v[214:217], v[8:11]
	v_mfma_f32_16x16x32_bf16 v[52:55], v[158:161], v[180:183], v[52:55]
	v_mfma_f32_16x16x32_bf16 v[48:51], v[172:175], v[180:183], v[48:51]
	v_mfma_f32_16x16x32_bf16 v[36:39], v[158:161], v[188:191], v[36:39]
	v_mfma_f32_16x16x32_bf16 v[32:35], v[172:175], v[188:191], v[32:35]
	v_mfma_f32_16x16x32_bf16 v[20:23], v[158:161], v[200:203], v[20:23]
	v_mfma_f32_16x16x32_bf16 v[16:19], v[172:175], v[200:203], v[16:19]
	v_mfma_f32_16x16x32_bf16 v[4:7], v[158:161], v[210:213], v[4:7]
	v_mfma_f32_16x16x32_bf16 v[0:3], v[172:175], v[210:213], v[0:3]
	v_mfma_f32_16x16x32_bf16 v[52:55], v[168:171], v[184:187], v[52:55]
	v_mfma_f32_16x16x32_bf16 v[48:51], v[176:179], v[184:187], v[48:51]
	v_mfma_f32_16x16x32_bf16 v[36:39], v[168:171], v[192:195], v[36:39]
	v_mfma_f32_16x16x32_bf16 v[32:35], v[176:179], v[192:195], v[32:35]
	v_mfma_f32_16x16x32_bf16 v[20:23], v[168:171], v[206:209], v[20:23]
	v_mfma_f32_16x16x32_bf16 v[16:19], v[176:179], v[206:209], v[16:19]
	v_mfma_f32_16x16x32_bf16 v[4:7], v[168:171], v[214:217], v[4:7]
	v_mfma_f32_16x16x32_bf16 v[0:3], v[176:179], v[214:217], v[0:3]
	s_barrier
	s_setprio 0
	s_add_i32 s35, 0, 0x18000
	v_add_u32_e32 v140, s35, v165
	s_add_i32 s60, 0, 0x1c000
	ds_read_b128 v[142:145], v140
	ds_read_b128 v[146:149], v140 offset:1024
	ds_read_b128 v[150:153], v140 offset:2048
	ds_read_b128 v[154:157], v140 offset:3072
	v_add_u32_e32 v140, s60, v165
	ds_read_b128 v[158:161], v140
	ds_read_b128 v[168:171], v140 offset:1024
	ds_read_b128 v[172:175], v140 offset:2048
	ds_read_b128 v[176:179], v140 offset:3072
	s_add_u32 s10, s10, 0x40000
	s_addc_u32 s11, s11, 0
	s_mov_b32 m0, s29
	v_lshl_add_u64 v[218:219], s[10:11], 0, v[134:135]
	ds_read_b128 v[180:183], v166 offset:32768
	ds_read_b128 v[184:187], v166 offset:33792
	ds_read_b128 v[188:191], v166 offset:34816
	ds_read_b128 v[192:195], v166 offset:35840
	ds_read_b128 v[200:203], v166 offset:36864
	ds_read_b128 v[206:209], v166 offset:37888
	ds_read_b128 v[210:213], v166 offset:38912
	ds_read_b128 v[214:217], v166 offset:39936
	global_load_lds_dwordx4 v[218:219], off
	v_lshl_add_u64 v[218:219], s[10:11], 0, v[130:131]
	s_mov_b32 m0, s38
	s_nop 0
	global_load_lds_dwordx4 v[218:219], off
	s_waitcnt vmcnt(8)
	s_waitcnt lgkmcnt(0)
	s_barrier
	v_mfma_f32_16x16x32_bf16 v[124:127], v[142:145], v[180:183], v[124:127]
	s_setprio 1
	v_mfma_f32_16x16x32_bf16 v[120:123], v[150:153], v[180:183], v[120:123]
	v_mfma_f32_16x16x32_bf16 v[108:111], v[142:145], v[188:191], v[108:111]
	v_mfma_f32_16x16x32_bf16 v[104:107], v[150:153], v[188:191], v[104:107]
	v_mfma_f32_16x16x32_bf16 v[92:95], v[142:145], v[200:203], v[92:95]
	v_mfma_f32_16x16x32_bf16 v[88:91], v[150:153], v[200:203], v[88:91]
	v_mfma_f32_16x16x32_bf16 v[76:79], v[142:145], v[210:213], v[76:79]
	v_mfma_f32_16x16x32_bf16 v[72:75], v[150:153], v[210:213], v[72:75]
	v_mfma_f32_16x16x32_bf16 v[124:127], v[146:149], v[184:187], v[124:127]
	v_mfma_f32_16x16x32_bf16 v[120:123], v[154:157], v[184:187], v[120:123]
	v_mfma_f32_16x16x32_bf16 v[108:111], v[146:149], v[192:195], v[108:111]
	v_mfma_f32_16x16x32_bf16 v[104:107], v[154:157], v[192:195], v[104:107]
	v_mfma_f32_16x16x32_bf16 v[92:95], v[146:149], v[206:209], v[92:95]
	v_mfma_f32_16x16x32_bf16 v[88:91], v[154:157], v[206:209], v[88:91]
	v_mfma_f32_16x16x32_bf16 v[76:79], v[146:149], v[214:217], v[76:79]
	v_mfma_f32_16x16x32_bf16 v[72:75], v[154:157], v[214:217], v[72:75]
	v_mfma_f32_16x16x32_bf16 v[116:119], v[158:161], v[180:183], v[116:119]
	v_mfma_f32_16x16x32_bf16 v[112:115], v[172:175], v[180:183], v[112:115]
	v_mfma_f32_16x16x32_bf16 v[100:103], v[158:161], v[188:191], v[100:103]
	v_mfma_f32_16x16x32_bf16 v[96:99], v[172:175], v[188:191], v[96:99]
	v_mfma_f32_16x16x32_bf16 v[84:87], v[158:161], v[200:203], v[84:87]
	v_mfma_f32_16x16x32_bf16 v[80:83], v[172:175], v[200:203], v[80:83]
	v_mfma_f32_16x16x32_bf16 v[68:71], v[158:161], v[210:213], v[68:71]
	v_mfma_f32_16x16x32_bf16 v[64:67], v[172:175], v[210:213], v[64:67]
	v_mfma_f32_16x16x32_bf16 v[116:119], v[168:171], v[184:187], v[116:119]
	v_mfma_f32_16x16x32_bf16 v[112:115], v[176:179], v[184:187], v[112:115]
	v_mfma_f32_16x16x32_bf16 v[100:103], v[168:171], v[192:195], v[100:103]
	v_mfma_f32_16x16x32_bf16 v[96:99], v[176:179], v[192:195], v[96:99]
	v_mfma_f32_16x16x32_bf16 v[84:87], v[168:171], v[206:209], v[84:87]
	v_mfma_f32_16x16x32_bf16 v[80:83], v[176:179], v[206:209], v[80:83]
	v_mfma_f32_16x16x32_bf16 v[68:71], v[168:171], v[214:217], v[68:71]
	v_mfma_f32_16x16x32_bf16 v[64:67], v[176:179], v[214:217], v[64:67]
	s_barrier
	s_setprio 0
	s_add_i32 s10, s35, s13
	v_lshl_add_u64 v[162:163], v[162:163], 0, s[36:37]
	s_mov_b32 m0, s10
	ds_read_b128 v[180:183], v166 offset:49152
	ds_read_b128 v[184:187], v166 offset:50176
	ds_read_b128 v[188:191], v166 offset:51200
	ds_read_b128 v[192:195], v166 offset:52224
	ds_read_b128 v[200:203], v166 offset:53248
	ds_read_b128 v[206:209], v166 offset:54272
	ds_read_b128 v[210:213], v166 offset:55296
	ds_read_b128 v[214:217], v166 offset:56320
	global_load_lds_dwordx4 v[162:163], off
	s_add_i32 m0, s10, 0x2000
	s_add_u32 s8, s8, 0x40080
	v_lshl_add_u64 v[162:163], v[196:197], 0, s[36:37]
	s_addc_u32 s9, s9, 0
	s_add_i32 s10, s60, s13
	global_load_lds_dwordx4 v[162:163], off
	v_lshl_add_u64 v[162:163], s[8:9], 0, v[132:133]
	s_mov_b32 m0, s10
	s_nop 0
	global_load_lds_dwordx4 v[162:163], off
	v_lshl_add_u64 v[162:163], s[8:9], 0, v[128:129]
	s_add_i32 m0, s10, 0x2000
	s_nop 0
	global_load_lds_dwordx4 v[162:163], off
	v_lshl_add_u64 v[162:163], v[198:199], 0, s[36:37]
	s_mov_b32 m0, s42
	s_nop 0
	global_load_lds_dwordx4 v[162:163], off
	v_lshl_add_u64 v[162:163], v[204:205], 0, s[36:37]
	s_mov_b32 m0, s43
	s_nop 0
	global_load_lds_dwordx4 v[162:163], off
	s_waitcnt vmcnt(8)
	s_waitcnt lgkmcnt(0)
	s_barrier
	v_mfma_f32_16x16x32_bf16 v[60:63], v[142:145], v[180:183], v[60:63]
	s_setprio 1
	v_mfma_f32_16x16x32_bf16 v[56:59], v[150:153], v[180:183], v[56:59]
	v_mfma_f32_16x16x32_bf16 v[44:47], v[142:145], v[188:191], v[44:47]
	v_mfma_f32_16x16x32_bf16 v[40:43], v[150:153], v[188:191], v[40:43]
	v_mfma_f32_16x16x32_bf16 v[28:31], v[142:145], v[200:203], v[28:31]
	v_mfma_f32_16x16x32_bf16 v[24:27], v[150:153], v[200:203], v[24:27]
	v_mfma_f32_16x16x32_bf16 v[12:15], v[142:145], v[210:213], v[12:15]
	v_mfma_f32_16x16x32_bf16 v[8:11], v[150:153], v[210:213], v[8:11]
	v_mfma_f32_16x16x32_bf16 v[60:63], v[146:149], v[184:187], v[60:63]
	v_mfma_f32_16x16x32_bf16 v[56:59], v[154:157], v[184:187], v[56:59]
	v_mfma_f32_16x16x32_bf16 v[44:47], v[146:149], v[192:195], v[44:47]
	v_mfma_f32_16x16x32_bf16 v[40:43], v[154:157], v[192:195], v[40:43]
	v_mfma_f32_16x16x32_bf16 v[28:31], v[146:149], v[206:209], v[28:31]
	v_mfma_f32_16x16x32_bf16 v[24:27], v[154:157], v[206:209], v[24:27]
	v_mfma_f32_16x16x32_bf16 v[12:15], v[146:149], v[214:217], v[12:15]
	v_mfma_f32_16x16x32_bf16 v[8:11], v[154:157], v[214:217], v[8:11]
	v_mfma_f32_16x16x32_bf16 v[52:55], v[158:161], v[180:183], v[52:55]
	v_mfma_f32_16x16x32_bf16 v[48:51], v[172:175], v[180:183], v[48:51]
	v_mfma_f32_16x16x32_bf16 v[36:39], v[158:161], v[188:191], v[36:39]
	v_mfma_f32_16x16x32_bf16 v[32:35], v[172:175], v[188:191], v[32:35]
	v_mfma_f32_16x16x32_bf16 v[20:23], v[158:161], v[200:203], v[20:23]
	v_mfma_f32_16x16x32_bf16 v[16:19], v[172:175], v[200:203], v[16:19]
	v_mfma_f32_16x16x32_bf16 v[4:7], v[158:161], v[210:213], v[4:7]
	v_mfma_f32_16x16x32_bf16 v[0:3], v[172:175], v[210:213], v[0:3]
	v_mfma_f32_16x16x32_bf16 v[52:55], v[168:171], v[184:187], v[52:55]
	v_mfma_f32_16x16x32_bf16 v[48:51], v[176:179], v[184:187], v[48:51]
	v_mfma_f32_16x16x32_bf16 v[36:39], v[168:171], v[192:195], v[36:39]
	v_mfma_f32_16x16x32_bf16 v[32:35], v[176:179], v[192:195], v[32:35]
	v_mfma_f32_16x16x32_bf16 v[20:23], v[168:171], v[206:209], v[20:23]
	v_mfma_f32_16x16x32_bf16 v[16:19], v[176:179], v[206:209], v[16:19]
	v_mfma_f32_16x16x32_bf16 v[4:7], v[168:171], v[214:217], v[4:7]
	v_mfma_f32_16x16x32_bf16 v[0:3], v[176:179], v[214:217], v[0:3]
	s_barrier
	s_setprio 0
	s_add_i32 s59, s59, 2
	s_add_u32 s6, s6, 0x100
	s_addc_u32 s7, s7, 0
	s_add_u32 s53, s53, 0x100
	s_addc_u32 s58, s58, 0
	s_cmp_gt_u32 s59, 13
	s_cbranch_scc0 .LBB0_92
	s_nop 0
	s_and_b64 vcc, exec, s[48:49]
	s_cbranch_vccz .LBB0_95
	s_barrier
